# baseline (speedup 1.0000x reference)
; #define GAS __attribute__((address_space(1)))
; __device__ __forceinline__ int ugrid() { return __builtin_amdgcn_readfirstlane((int)gridDim.x); }
; __device__ __forceinline__ int ubid() { return __builtin_amdgcn_readfirstlane((int)blockIdx.x); }
; __device__ __forceinline__ void phase_inproj() {
;     ...
;       for (int r0 = ubid() * 64 + w * 16; r0 < T; r0 += ugrid() * 64) {
;         const GAS bf16x8* ap = (const GAS bf16x8*)(xg + (size_t)(r0 + fr_) * DM + fq_ * 8);
;         const GAS bf16x8* bp = (const GAS bf16x8*)(wf + (size_t)(fr_ & 7) * DM + fq_ * 8);
;         f32x4 c = {0.f, 0.f, 0.f, 0.f};
; #pragma unroll
;         for (int kb = 0; kb < 2; ++kb) {
;           bf16x8 a[16], b[16];
; #pragma unroll
;           for (int k = 0; k < 16; ++k) { a[k] = ap[(kb * 16 + k) * 4]; b[k] = bp[(kb * 16 + k) * 4]; }
; #pragma unroll
;           for (int k = 0; k < 16; ++k) c = __builtin_amdgcn_mfma_f32_16x16x32_bf16(a[k], b[k], c, 0, 0, 0);
;         }
.LBB0_378:
	v_or_b32_e32 v2, v7, v6
	v_ashrrev_i32_e32 v3, 31, v2
	v_lshlrev_b64 v[2:3], 11, v[2:3]
	v_lshl_add_u64 v[86:87], v[10:11], 0, v[2:3]
	global_load_dwordx4 v[14:17], v[86:87], off
	global_load_dwordx4 v[26:29], v[12:13], off
	global_load_dwordx4 v[30:33], v[86:87], off offset:64
	global_load_dwordx4 v[34:37], v[12:13], off offset:64
	global_load_dwordx4 v[38:41], v[86:87], off offset:128
	global_load_dwordx4 v[42:45], v[12:13], off offset:128
	global_load_dwordx4 v[46:49], v[86:87], off offset:192
	global_load_dwordx4 v[50:53], v[12:13], off offset:192
	global_load_dwordx4 v[54:57], v[86:87], off offset:256
	global_load_dwordx4 v[58:61], v[12:13], off offset:256
	global_load_dwordx4 v[62:65], v[86:87], off offset:320
	global_load_dwordx4 v[66:69], v[12:13], off offset:320
	global_load_dwordx4 v[70:73], v[86:87], off offset:384
	global_load_dwordx4 v[74:77], v[12:13], off offset:384
	global_load_dwordx4 v[78:81], v[86:87], off offset:448
	global_load_dwordx4 v[82:85], v[12:13], off offset:448
	global_load_dwordx4 v[88:91], v[86:87], off offset:512
	global_load_dwordx4 v[92:95], v[12:13], off offset:512
	global_load_dwordx4 v[96:99], v[86:87], off offset:576
	global_load_dwordx4 v[100:103], v[12:13], off offset:576
	global_load_dwordx4 v[104:107], v[86:87], off offset:640
	global_load_dwordx4 v[108:111], v[12:13], off offset:640
	global_load_dwordx4 v[112:115], v[86:87], off offset:704
	global_load_dwordx4 v[116:119], v[12:13], off offset:704
	global_load_dwordx4 v[120:123], v[86:87], off offset:768
	global_load_dwordx4 v[124:127], v[12:13], off offset:768
	global_load_dwordx4 v[128:131], v[86:87], off offset:832
	global_load_dwordx4 v[132:135], v[12:13], off offset:832
	global_load_dwordx4 v[136:139], v[86:87], off offset:896
	global_load_dwordx4 v[140:143], v[12:13], off offset:896
	global_load_dwordx4 v[144:147], v[86:87], off offset:960
	global_load_dwordx4 v[148:151], v[12:13], off offset:960
	global_load_dwordx4 v[152:155], v[86:87], off offset:1024
	global_load_dwordx4 v[156:159], v[12:13], off offset:1024
	global_load_dwordx4 v[160:163], v[86:87], off offset:1088
	global_load_dwordx4 v[164:167], v[12:13], off offset:1088
	global_load_dwordx4 v[176:179], v[86:87], off offset:1152
	global_load_dwordx4 v[180:183], v[12:13], off offset:1152
	global_load_dwordx4 v[184:187], v[86:87], off offset:1216
	global_load_dwordx4 v[188:191], v[12:13], off offset:1216
	global_load_dwordx4 v[192:195], v[86:87], off offset:1280
	global_load_dwordx4 v[196:199], v[12:13], off offset:1280
	global_load_dwordx4 v[200:203], v[86:87], off offset:1344
	global_load_dwordx4 v[204:207], v[12:13], off offset:1344
	global_load_dwordx4 v[208:211], v[86:87], off offset:1408
	global_load_dwordx4 v[212:215], v[12:13], off offset:1408
	global_load_dwordx4 v[216:219], v[86:87], off offset:1472
	global_load_dwordx4 v[220:223], v[12:13], off offset:1472
	global_load_dwordx4 v[224:227], v[86:87], off offset:1536
	global_load_dwordx4 v[228:231], v[12:13], off offset:1536
	global_load_dwordx4 v[232:235], v[86:87], off offset:1600
	global_load_dwordx4 v[236:239], v[12:13], off offset:1600
	s_waitcnt vmcnt(40)
	v_mfma_f32_16x16x32_bf16 v[2:5], v[14:17], v[26:29], 0
	v_mfma_f32_16x16x32_bf16 v[2:5], v[30:33], v[34:37], v[2:5]
	v_mfma_f32_16x16x32_bf16 v[2:5], v[38:41], v[42:45], v[2:5]
	v_mfma_f32_16x16x32_bf16 v[2:5], v[46:49], v[50:53], v[2:5]
	v_mfma_f32_16x16x32_bf16 v[2:5], v[54:57], v[58:61], v[2:5]
	v_mfma_f32_16x16x32_bf16 v[2:5], v[62:65], v[66:69], v[2:5]
	global_load_dwordx4 v[14:17], v[86:87], off offset:1664
	global_load_dwordx4 v[26:29], v[12:13], off offset:1664
	global_load_dwordx4 v[30:33], v[86:87], off offset:1728
	global_load_dwordx4 v[34:37], v[12:13], off offset:1728
	global_load_dwordx4 v[38:41], v[86:87], off offset:1792
	global_load_dwordx4 v[42:45], v[12:13], off offset:1792
	global_load_dwordx4 v[46:49], v[86:87], off offset:1856
	global_load_dwordx4 v[50:53], v[12:13], off offset:1856
	global_load_dwordx4 v[54:57], v[86:87], off offset:1920
	global_load_dwordx4 v[58:61], v[12:13], off offset:1920
	global_load_dwordx4 v[62:65], v[86:87], off offset:1984
	global_load_dwordx4 v[66:69], v[12:13], off offset:1984
	s_waitcnt vmcnt(50)
	v_mfma_f32_16x16x32_bf16 v[2:5], v[70:73], v[74:77], v[2:5]
	s_waitcnt vmcnt(48)
	v_mfma_f32_16x16x32_bf16 v[2:5], v[78:81], v[82:85], v[2:5]
	s_waitcnt vmcnt(46)
	v_mfma_f32_16x16x32_bf16 v[2:5], v[88:91], v[92:95], v[2:5]
	s_waitcnt vmcnt(44)
	v_mfma_f32_16x16x32_bf16 v[2:5], v[96:99], v[100:103], v[2:5]
	s_waitcnt vmcnt(42)
	v_mfma_f32_16x16x32_bf16 v[2:5], v[104:107], v[108:111], v[2:5]
	s_waitcnt vmcnt(40)
	v_mfma_f32_16x16x32_bf16 v[2:5], v[112:115], v[116:119], v[2:5]
	s_waitcnt vmcnt(38)
	v_mfma_f32_16x16x32_bf16 v[2:5], v[120:123], v[124:127], v[2:5]
	s_waitcnt vmcnt(36)
	v_mfma_f32_16x16x32_bf16 v[2:5], v[128:131], v[132:135], v[2:5]
	s_waitcnt vmcnt(34)
	v_mfma_f32_16x16x32_bf16 v[2:5], v[136:139], v[140:143], v[2:5]
	s_waitcnt vmcnt(32)
	v_mfma_f32_16x16x32_bf16 v[2:5], v[144:147], v[148:151], v[2:5]
	s_waitcnt vmcnt(30)
	v_mfma_f32_16x16x32_bf16 v[2:5], v[152:155], v[156:159], v[2:5]
	s_waitcnt vmcnt(28)
	v_mfma_f32_16x16x32_bf16 v[2:5], v[160:163], v[164:167], v[2:5]
	s_waitcnt vmcnt(26)
	v_mfma_f32_16x16x32_bf16 v[2:5], v[176:179], v[180:183], v[2:5]
	s_waitcnt vmcnt(24)
	v_mfma_f32_16x16x32_bf16 v[2:5], v[184:187], v[188:191], v[2:5]
	s_waitcnt vmcnt(22)
	v_mfma_f32_16x16x32_bf16 v[2:5], v[192:195], v[196:199], v[2:5]
	s_waitcnt vmcnt(20)
	v_mfma_f32_16x16x32_bf16 v[2:5], v[200:203], v[204:207], v[2:5]
	s_waitcnt vmcnt(18)
	v_mfma_f32_16x16x32_bf16 v[2:5], v[208:211], v[212:215], v[2:5]
	s_waitcnt vmcnt(16)
	v_mfma_f32_16x16x32_bf16 v[2:5], v[216:219], v[220:223], v[2:5]
	s_waitcnt vmcnt(14)
	v_mfma_f32_16x16x32_bf16 v[2:5], v[224:227], v[228:231], v[2:5]
	s_waitcnt vmcnt(12)
	v_mfma_f32_16x16x32_bf16 v[2:5], v[232:235], v[236:239], v[2:5]
	s_waitcnt vmcnt(10)
	v_mfma_f32_16x16x32_bf16 v[2:5], v[14:17], v[26:29], v[2:5]
	s_waitcnt vmcnt(8)
	v_mfma_f32_16x16x32_bf16 v[2:5], v[30:33], v[34:37], v[2:5]
	s_waitcnt vmcnt(6)
	v_mfma_f32_16x16x32_bf16 v[2:5], v[38:41], v[42:45], v[2:5]
	s_waitcnt vmcnt(4)
	v_mfma_f32_16x16x32_bf16 v[2:5], v[46:49], v[50:53], v[2:5]
	s_waitcnt vmcnt(2)
	v_mfma_f32_16x16x32_bf16 v[2:5], v[54:57], v[58:61], v[2:5]
	s_waitcnt vmcnt(0)
	v_mfma_f32_16x16x32_bf16 v[2:5], v[62:65], v[66:69], v[2:5]
	s_and_saveexec_b64 s[12:13], vcc
	s_cbranch_execz .LBB0_377
; #define GAS __attribute__((address_space(1)))
; __device__ __forceinline__ void phase_inproj() {
;     ...
;         if (fr_ < 8) {
;           const float bias = ((const GAS float*)P.forget_bias)[fr_];
; #pragma unroll
;           for (int i = 0; i < 4; ++i) {
;             const int row = r0 + fq_ * 4 + i;
;             const GAS f32x4* sp = (const GAS f32x4*)(ssq + (size_t)row * 16);
;             const f32x4 s0 = sp[0], s1 = sp[1], s2 = sp[2], s3 = sp[3];
;             const float t = ((s0.x + s0.y) + (s0.z + s0.w)) + ((s1.x + s1.y) + (s1.z + s1.w)) + ((s2.x + s2.y) + (s2.z + s2.w)) + ((s3.x + s3.y) + (s3.z + s3.w));
;             const float l = c[i] * rsqrtf(t * (1.f / DM) + EPS) + bias;
;             const float ls = fminf(l, 0.f) - log1pf(__expf(-fabsf(l)));
;             logf2[(size_t)((row >> 13) * 8 + fr_) * SEQ + (row & (SEQ - 1))] = ls * LOG2E;
;           }
	v_or_b32_e32 v14, v7, v18
	v_ashrrev_i32_e32 v15, 31, v14
	v_lshlrev_b64 v[16:17], 6, v[14:15]
	v_lshl_add_u64 v[16:17], s[8:9], 0, v[16:17]
	global_load_dwordx4 v[26:29], v[16:17], off
	global_load_dwordx4 v[30:33], v[16:17], off offset:16
	global_load_dwordx4 v[34:37], v[16:17], off offset:32
	global_load_dwordx4 v[38:41], v[16:17], off offset:48
	s_load_dwordx2 s[4:5], s[6:7], 0x40
	v_ashrrev_i32_e32 v8, 10, v7
	v_bitop3_b32 v17, v7, s23, v18 bitop3:0xc8
	v_and_or_b32 v16, v8, -8, v6
	v_lshlrev_b32_e32 v8, 2, v17
	s_waitcnt lgkmcnt(0)
	global_load_dword v15, v19, s[4:5]
	v_or_b32_e32 v42, 1, v14
	v_ashrrev_i32_e32 v17, 31, v16
	v_ashrrev_i32_e32 v43, 31, v42
	v_lshlrev_b64 v[16:17], 15, v[16:17]
	v_lshl_add_u64 v[16:17], s[16:17], 0, v[16:17]
	s_waitcnt vmcnt(4)
	v_mov_b32_e32 v44, v27
	v_mov_b32_e32 v45, v28
	v_mov_b32_e32 v27, v29
	s_waitcnt vmcnt(3)
	v_mov_b32_e32 v28, v31
	v_mov_b32_e32 v29, v32
	v_mov_b32_e32 v31, v33
	v_pk_add_f32 v[26:27], v[44:45], v[26:27]
	v_pk_add_f32 v[28:29], v[28:29], v[30:31]
	v_pk_add_f32 v[26:27], v[26:27], v[26:27] op_sel:[0,1] op_sel_hi:[1,0]
	v_pk_add_f32 v[28:29], v[28:29], v[28:29] op_sel:[0,1] op_sel_hi:[1,0]
	s_waitcnt vmcnt(2)
	v_add_f32_e32 v32, v34, v35
	v_add_f32_e32 v34, v36, v37
	s_waitcnt vmcnt(1)
	v_mov_b32_e32 v33, v40
	v_mov_b32_e32 v35, v41
	v_mov_b32_e32 v27, v38
	v_mov_b32_e32 v29, v39
	v_pk_add_f32 v[30:31], v[32:33], v[34:35]
	v_pk_add_f32 v[26:27], v[26:27], v[28:29]
	s_nop 0
	v_pk_add_f32 v[26:27], v[26:27], v[30:31]
	s_nop 0
	v_add_f32_e32 v25, v26, v27
	v_fmamk_f32 v25, v25, 0x3a800000, v20
	v_mul_f32_e32 v26, 0x4b800000, v25
	v_cmp_gt_f32_e64 s[4:5], s3, v25
	s_nop 1
	v_cndmask_b32_e64 v25, v25, v26, s[4:5]
	v_rsq_f32_e32 v25, v25
	v_lshlrev_b64 v[26:27], 6, v[42:43]
	v_lshl_add_u64 v[42:43], s[8:9], 0, v[26:27]
	v_lshl_add_u64 v[26:27], v[16:17], 0, v[8:9]
	v_mul_f32_e32 v28, 0x45800000, v25
	v_cndmask_b32_e64 v25, v25, v28, s[4:5]
	s_waitcnt vmcnt(0)
	v_fma_f32 v2, v2, v25, v15
	v_mul_f32_e64 v25, |v2|, s18
	v_exp_f32_e32 v25, v25
	v_min_f32_e32 v2, 0, v2
	v_add_f32_e32 v8, 1.0, v25
	v_add_f32_e32 v30, -1.0, v8
	v_frexp_mant_f32_e32 v31, v8
	v_cvt_f64_f32_e32 v[28:29], v8
	v_sub_f32_e32 v32, v30, v8
	v_frexp_exp_i32_f64_e32 v28, v[28:29]
	v_cmp_gt_f32_e64 s[4:5], s19, v31
	v_sub_f32_e32 v30, v25, v30
	v_add_f32_e32 v29, 1.0, v32
	v_subbrev_co_u32_e64 v28, s[4:5], 0, v28, s[4:5]
	v_add_f32_e32 v29, v30, v29
	v_sub_u32_e32 v30, 0, v28
	v_cvt_f32_i32_e32 v28, v28
	v_ldexp_f32 v8, v8, v30
	v_ldexp_f32 v29, v29, v30
	v_add_f32_e32 v30, -1.0, v8
	v_add_f32_e32 v31, 1.0, v8
	v_add_f32_e32 v32, 1.0, v30
	v_add_f32_e32 v33, -1.0, v31
	v_sub_f32_e32 v32, v8, v32
	v_sub_f32_e32 v8, v8, v33
	v_mul_f32_e32 v33, 0x3f317218, v28
	v_add_f32_e32 v32, v29, v32
	v_add_f32_e32 v8, v29, v8
	v_fma_f32 v29, v28, s20, -v33
	v_add_f32_e32 v34, v30, v32
	v_add_f32_e32 v35, v31, v8
	v_fmac_f32_e32 v29, 0xb102e308, v28
	v_sub_f32_e32 v28, v34, v30
	v_sub_f32_e32 v30, v35, v31
	v_rcp_f32_e32 v31, v35
	v_add_f32_e32 v36, v33, v29
	v_sub_f32_e32 v8, v8, v30
	v_sub_f32_e32 v30, v36, v33
	v_sub_f32_e32 v29, v29, v30
	v_mul_f32_e32 v30, v34, v31
	v_sub_f32_e32 v28, v32, v28
	v_mul_f32_e32 v32, v35, v30
	v_fma_f32 v33, v30, v35, -v32
	v_fmac_f32_e32 v33, v30, v8
	v_add_f32_e32 v37, v32, v33
	v_sub_f32_e32 v38, v34, v37
	v_sub_f32_e32 v32, v37, v32
	v_sub_f32_e32 v34, v34, v38
	v_sub_f32_e32 v32, v32, v33
	v_sub_f32_e32 v33, v34, v37
	v_add_f32_e32 v28, v28, v33
	v_add_f32_e32 v28, v32, v28
	v_add_f32_e32 v32, v38, v28
	v_mul_f32_e32 v33, v31, v32
	v_sub_f32_e32 v34, v38, v32
	v_mul_f32_e32 v37, v35, v33
	v_add_f32_e32 v28, v28, v34
	v_add_f32_e32 v34, v30, v33
	v_fma_f32 v35, v33, v35, -v37
	v_sub_f32_e32 v30, v34, v30
	v_fmac_f32_e32 v35, v33, v8
	v_sub_f32_e32 v8, v33, v30
	v_add_f32_e32 v30, v37, v35
	v_sub_f32_e32 v33, v30, v37
	v_sub_f32_e32 v37, v32, v30
	v_sub_f32_e32 v32, v32, v37
	v_sub_f32_e32 v30, v32, v30
	v_sub_f32_e32 v33, v33, v35
	v_add_f32_e32 v28, v28, v30
	v_add_f32_e32 v28, v33, v28
	v_add_f32_e32 v28, v37, v28
	v_mul_f32_e32 v28, v31, v28
	v_add_f32_e32 v8, v8, v28
	v_add_f32_e32 v28, v34, v8
	v_mul_f32_e32 v30, v28, v28
	v_fmamk_f32 v33, v30, 0x3e9b6dac, v21
	v_sub_f32_e32 v31, v28, v34
	v_ldexp_f32 v32, v28, 1
	v_mul_f32_e32 v28, v28, v30
	v_fmaak_f32 v30, v30, v33, 0x3f2aaada
	v_mul_f32_e32 v28, v28, v30
	v_add_f32_e32 v30, v32, v28
	v_sub_f32_e32 v8, v8, v31
	v_sub_f32_e32 v31, v30, v32
	v_ldexp_f32 v8, v8, 1
	v_sub_f32_e32 v28, v28, v31
	v_add_f32_e32 v8, v8, v28
	v_add_f32_e32 v28, v30, v8
	v_sub_f32_e32 v30, v28, v30
	v_add_f32_e32 v31, v36, v28
	v_sub_f32_e32 v8, v8, v30
	v_sub_f32_e32 v30, v31, v36
	v_sub_f32_e32 v32, v31, v30
	v_sub_f32_e32 v28, v28, v30
	v_add_f32_e32 v30, v29, v8
	v_sub_f32_e32 v32, v36, v32
	v_sub_f32_e32 v33, v30, v29
	v_add_f32_e32 v28, v28, v32
	v_sub_f32_e32 v32, v30, v33
	v_sub_f32_e32 v8, v8, v33
	v_sub_f32_e32 v29, v29, v32
	v_add_f32_e32 v28, v30, v28
	v_add_f32_e32 v8, v8, v29
	v_add_f32_e32 v29, v31, v28
	v_sub_f32_e32 v30, v29, v31
	v_sub_f32_e32 v28, v28, v30
	v_add_f32_e32 v8, v8, v28
	v_add_f32_e32 v8, v29, v8
	v_cmp_neq_f32_e64 s[4:5], s21, v25
	s_nop 1
	v_cndmask_b32_e64 v8, v22, v8, s[4:5]
	v_cmp_ngt_f32_e64 s[4:5], -1.0, v25
	s_nop 1
	v_cndmask_b32_e64 v8, v23, v8, s[4:5]
	v_cmp_neq_f32_e64 s[4:5], -1.0, v25
	s_nop 1
	v_cndmask_b32_e64 v8, v24, v8, s[4:5]
	v_cmp_lt_f32_e64 s[4:5], |v25|, s22
	s_nop 1
	v_cndmask_b32_e64 v8, v8, v25, s[4:5]
	v_sub_f32_e32 v2, v2, v8
	v_mul_f32_e32 v2, 0x3fb8aa3b, v2
	global_store_dword v[26:27], v2, off
	global_load_dwordx4 v[26:29], v[42:43], off
	s_nop 0
	global_load_dwordx4 v[30:33], v[42:43], off offset:16
	global_load_dwordx4 v[34:37], v[42:43], off offset:32
	global_load_dwordx4 v[38:41], v[42:43], off offset:48
	v_bitop3_b32 v2, v14, s24, 1 bitop3:0xc8
	v_or_b32_e32 v42, 2, v14
	v_ashrrev_i32_e32 v43, 31, v42
	s_waitcnt vmcnt(3)
; #define GAS __attribute__((address_space(1)))
; __device__ __forceinline__ void phase_inproj() {
;     ...
;         if (fr_ < 8) {
;           const float bias = ((const GAS float*)P.forget_bias)[fr_];
; #pragma unroll
;           for (int i = 0; i < 4; ++i) {
;             const int row = r0 + fq_ * 4 + i;
;             const GAS f32x4* sp = (const GAS f32x4*)(ssq + (size_t)row * 16);
;             const f32x4 s0 = sp[0], s1 = sp[1], s2 = sp[2], s3 = sp[3];
;             const float t = ((s0.x + s0.y) + (s0.z + s0.w)) + ((s1.x + s1.y) + (s1.z + s1.w)) + ((s2.x + s2.y) + (s2.z + s2.w)) + ((s3.x + s3.y) + (s3.z + s3.w));
;             const float l = c[i] * rsqrtf(t * (1.f / DM) + EPS) + bias;
;             const float ls = fminf(l, 0.f) - log1pf(__expf(-fabsf(l)));
;             logf2[(size_t)((row >> 13) * 8 + fr_) * SEQ + (row & (SEQ - 1))] = ls * LOG2E;
;           }
	v_mov_b32_e32 v44, v27
	v_mov_b32_e32 v45, v28
	v_mov_b32_e32 v27, v29
	s_waitcnt vmcnt(2)
	v_mov_b32_e32 v28, v31
	v_mov_b32_e32 v29, v32
	v_mov_b32_e32 v31, v33
	v_pk_add_f32 v[26:27], v[44:45], v[26:27]
	v_pk_add_f32 v[28:29], v[28:29], v[30:31]
	v_pk_add_f32 v[26:27], v[26:27], v[26:27] op_sel:[0,1] op_sel_hi:[1,0]
	v_pk_add_f32 v[28:29], v[28:29], v[28:29] op_sel:[0,1] op_sel_hi:[1,0]
	s_waitcnt vmcnt(1)
	v_add_f32_e32 v32, v34, v35
	v_add_f32_e32 v34, v36, v37
	s_waitcnt vmcnt(0)
	v_mov_b32_e32 v33, v40
	v_mov_b32_e32 v35, v41
	v_mov_b32_e32 v27, v38
	v_mov_b32_e32 v29, v39
	v_pk_add_f32 v[30:31], v[32:33], v[34:35]
	v_pk_add_f32 v[26:27], v[26:27], v[28:29]
	s_nop 0
	v_pk_add_f32 v[26:27], v[26:27], v[30:31]
	s_nop 0
	v_add_f32_e32 v8, v26, v27
	v_fmamk_f32 v8, v8, 0x3a800000, v20
	v_mul_f32_e32 v25, 0x4b800000, v8
	v_cmp_gt_f32_e64 s[4:5], s3, v8
	v_lshlrev_b64 v[26:27], 6, v[42:43]
	v_lshl_add_u64 v[42:43], s[8:9], 0, v[26:27]
	v_cndmask_b32_e64 v8, v8, v25, s[4:5]
	v_rsq_f32_e32 v8, v8
	s_nop 0
	v_mul_f32_e32 v25, 0x45800000, v8
	v_cndmask_b32_e64 v8, v8, v25, s[4:5]
	v_fma_f32 v25, v3, v8, v15
	v_mul_f32_e64 v3, |v25|, s18
	v_exp_f32_e32 v28, v3
	v_lshlrev_b32_e32 v8, 2, v2
	v_lshl_add_u64 v[2:3], v[16:17], 0, v[8:9]
	v_min_f32_e32 v8, 0, v25
	v_add_f32_e32 v25, 1.0, v28
	v_add_f32_e32 v29, -1.0, v25
	v_frexp_mant_f32_e32 v30, v25
	v_cvt_f64_f32_e32 v[26:27], v25
	v_sub_f32_e32 v31, v29, v25
	v_frexp_exp_i32_f64_e32 v26, v[26:27]
	v_cmp_gt_f32_e64 s[4:5], s19, v30
	v_sub_f32_e32 v29, v28, v29
	v_add_f32_e32 v27, 1.0, v31
	v_subbrev_co_u32_e64 v26, s[4:5], 0, v26, s[4:5]
	v_add_f32_e32 v27, v29, v27
	v_sub_u32_e32 v29, 0, v26
	v_cvt_f32_i32_e32 v26, v26
	v_ldexp_f32 v25, v25, v29
	v_ldexp_f32 v27, v27, v29
	v_add_f32_e32 v29, -1.0, v25
	v_add_f32_e32 v30, 1.0, v25
	v_add_f32_e32 v31, 1.0, v29
	v_add_f32_e32 v32, -1.0, v30
	v_sub_f32_e32 v31, v25, v31
	v_sub_f32_e32 v25, v25, v32
	v_mul_f32_e32 v32, 0x3f317218, v26
	v_add_f32_e32 v31, v27, v31
	v_add_f32_e32 v25, v27, v25
	v_fma_f32 v27, v26, s20, -v32
	v_add_f32_e32 v33, v29, v31
	v_add_f32_e32 v34, v30, v25
	v_fmac_f32_e32 v27, 0xb102e308, v26
	v_sub_f32_e32 v26, v33, v29
	v_sub_f32_e32 v29, v34, v30
	v_rcp_f32_e32 v30, v34
	v_add_f32_e32 v35, v32, v27
	v_sub_f32_e32 v25, v25, v29
	v_sub_f32_e32 v29, v35, v32
	v_sub_f32_e32 v27, v27, v29
	v_mul_f32_e32 v29, v33, v30
	v_sub_f32_e32 v26, v31, v26
	v_mul_f32_e32 v31, v34, v29
	v_fma_f32 v32, v29, v34, -v31
	v_fmac_f32_e32 v32, v29, v25
	v_add_f32_e32 v36, v31, v32
	v_sub_f32_e32 v37, v33, v36
	v_sub_f32_e32 v31, v36, v31
	v_sub_f32_e32 v33, v33, v37
	v_sub_f32_e32 v31, v31, v32
	v_sub_f32_e32 v32, v33, v36
	v_add_f32_e32 v26, v26, v32
	v_add_f32_e32 v26, v31, v26
	v_add_f32_e32 v31, v37, v26
	v_mul_f32_e32 v32, v30, v31
	v_sub_f32_e32 v33, v37, v31
	v_mul_f32_e32 v36, v34, v32
	v_add_f32_e32 v26, v26, v33
	v_add_f32_e32 v33, v29, v32
	v_fma_f32 v34, v32, v34, -v36
	v_sub_f32_e32 v29, v33, v29
	v_fmac_f32_e32 v34, v32, v25
	v_sub_f32_e32 v25, v32, v29
	v_add_f32_e32 v29, v36, v34
	v_sub_f32_e32 v32, v29, v36
	v_sub_f32_e32 v36, v31, v29
	v_sub_f32_e32 v31, v31, v36
	v_sub_f32_e32 v29, v31, v29
	v_sub_f32_e32 v32, v32, v34
	v_add_f32_e32 v26, v26, v29
	v_add_f32_e32 v26, v32, v26
	v_add_f32_e32 v26, v36, v26
	v_mul_f32_e32 v26, v30, v26
	v_add_f32_e32 v25, v25, v26
	v_add_f32_e32 v26, v33, v25
	v_mul_f32_e32 v29, v26, v26
	v_fmamk_f32 v32, v29, 0x3e9b6dac, v21
	v_sub_f32_e32 v30, v26, v33
	v_ldexp_f32 v31, v26, 1
	v_mul_f32_e32 v26, v26, v29
	v_fmaak_f32 v29, v29, v32, 0x3f2aaada
	v_mul_f32_e32 v26, v26, v29
	v_add_f32_e32 v29, v31, v26
	v_sub_f32_e32 v25, v25, v30
	v_sub_f32_e32 v30, v29, v31
	v_ldexp_f32 v25, v25, 1
	v_sub_f32_e32 v26, v26, v30
	v_add_f32_e32 v25, v25, v26
	v_add_f32_e32 v26, v29, v25
	v_sub_f32_e32 v29, v26, v29
	v_add_f32_e32 v30, v35, v26
	v_sub_f32_e32 v25, v25, v29
	v_sub_f32_e32 v29, v30, v35
	v_sub_f32_e32 v31, v30, v29
	v_sub_f32_e32 v26, v26, v29
	v_add_f32_e32 v29, v27, v25
	v_sub_f32_e32 v31, v35, v31
	v_sub_f32_e32 v32, v29, v27
	v_add_f32_e32 v26, v26, v31
	v_sub_f32_e32 v31, v29, v32
	v_sub_f32_e32 v25, v25, v32
	v_sub_f32_e32 v27, v27, v31
	v_add_f32_e32 v26, v29, v26
	v_add_f32_e32 v25, v25, v27
	v_add_f32_e32 v27, v30, v26
	v_sub_f32_e32 v29, v27, v30
	v_sub_f32_e32 v26, v26, v29
	v_add_f32_e32 v25, v25, v26
	v_add_f32_e32 v25, v27, v25
	v_cmp_neq_f32_e64 s[4:5], s21, v28
	s_nop 1
	v_cndmask_b32_e64 v25, v22, v25, s[4:5]
	v_cmp_ngt_f32_e64 s[4:5], -1.0, v28
	s_nop 1
	v_cndmask_b32_e64 v25, v23, v25, s[4:5]
	v_cmp_neq_f32_e64 s[4:5], -1.0, v28
	s_nop 1
	v_cndmask_b32_e64 v25, v24, v25, s[4:5]
	v_cmp_lt_f32_e64 s[4:5], |v28|, s22
	s_nop 1
	v_cndmask_b32_e64 v25, v25, v28, s[4:5]
	v_sub_f32_e32 v8, v8, v25
	v_mul_f32_e32 v8, 0x3fb8aa3b, v8
	global_store_dword v[2:3], v8, off
	global_load_dwordx4 v[26:29], v[42:43], off
	global_load_dwordx4 v[30:33], v[42:43], off offset:16
	global_load_dwordx4 v[34:37], v[42:43], off offset:32
	global_load_dwordx4 v[38:41], v[42:43], off offset:48
	v_bitop3_b32 v8, v14, s25, 2 bitop3:0xc8
	v_lshlrev_b32_e32 v8, 2, v8
	v_or_b32_e32 v2, 3, v14
	s_waitcnt vmcnt(3)
	v_mov_b32_e32 v42, v27
	v_mov_b32_e32 v43, v28
	v_mov_b32_e32 v27, v29
	s_waitcnt vmcnt(2)
	v_mov_b32_e32 v28, v31
	v_mov_b32_e32 v29, v32
	v_mov_b32_e32 v31, v33
	v_pk_add_f32 v[26:27], v[42:43], v[26:27]
	v_pk_add_f32 v[28:29], v[28:29], v[30:31]
	v_pk_add_f32 v[26:27], v[26:27], v[26:27] op_sel:[0,1] op_sel_hi:[1,0]
	v_pk_add_f32 v[28:29], v[28:29], v[28:29] op_sel:[0,1] op_sel_hi:[1,0]
	s_waitcnt vmcnt(1)
	v_add_f32_e32 v32, v34, v35
	v_add_f32_e32 v34, v36, v37
	s_waitcnt vmcnt(0)
; #define GAS __attribute__((address_space(1)))
; __device__ __forceinline__ void phase_inproj() {
;     ...
;         if (fr_ < 8) {
;           const float bias = ((const GAS float*)P.forget_bias)[fr_];
; #pragma unroll
;           for (int i = 0; i < 4; ++i) {
;             const int row = r0 + fq_ * 4 + i;
;             const GAS f32x4* sp = (const GAS f32x4*)(ssq + (size_t)row * 16);
;             const f32x4 s0 = sp[0], s1 = sp[1], s2 = sp[2], s3 = sp[3];
;             const float t = ((s0.x + s0.y) + (s0.z + s0.w)) + ((s1.x + s1.y) + (s1.z + s1.w)) + ((s2.x + s2.y) + (s2.z + s2.w)) + ((s3.x + s3.y) + (s3.z + s3.w));
;             const float l = c[i] * rsqrtf(t * (1.f / DM) + EPS) + bias;
;             const float ls = fminf(l, 0.f) - log1pf(__expf(-fabsf(l)));
;             logf2[(size_t)((row >> 13) * 8 + fr_) * SEQ + (row & (SEQ - 1))] = ls * LOG2E;
;           }
	v_mov_b32_e32 v33, v40
	v_mov_b32_e32 v35, v41
	v_mov_b32_e32 v27, v38
	v_mov_b32_e32 v29, v39
	v_pk_add_f32 v[30:31], v[32:33], v[34:35]
	v_pk_add_f32 v[26:27], v[26:27], v[28:29]
	s_nop 0
	v_pk_add_f32 v[26:27], v[26:27], v[30:31]
	s_nop 0
	v_add_f32_e32 v3, v26, v27
	v_fmamk_f32 v3, v3, 0x3a800000, v20
	v_mul_f32_e32 v25, 0x4b800000, v3
	v_cmp_gt_f32_e64 s[4:5], s3, v3
	s_nop 1
	v_cndmask_b32_e64 v3, v3, v25, s[4:5]
	v_rsq_f32_e32 v25, v3
	v_ashrrev_i32_e32 v3, 31, v2
	v_lshlrev_b64 v[2:3], 6, v[2:3]
	v_lshl_add_u64 v[2:3], s[8:9], 0, v[2:3]
	v_mul_f32_e32 v26, 0x45800000, v25
	v_cndmask_b32_e64 v25, v25, v26, s[4:5]
	v_fma_f32 v4, v4, v25, v15
	v_mul_f32_e64 v25, |v4|, s18
	v_exp_f32_e32 v25, v25
	v_lshl_add_u64 v[26:27], v[16:17], 0, v[8:9]
	v_min_f32_e32 v4, 0, v4
	v_add_f32_e32 v8, 1.0, v25
	v_add_f32_e32 v30, -1.0, v8
	v_frexp_mant_f32_e32 v31, v8
	v_cvt_f64_f32_e32 v[28:29], v8
	v_sub_f32_e32 v32, v30, v8
	v_frexp_exp_i32_f64_e32 v28, v[28:29]
	v_cmp_gt_f32_e64 s[4:5], s19, v31
	v_sub_f32_e32 v30, v25, v30
	v_add_f32_e32 v29, 1.0, v32
	v_subbrev_co_u32_e64 v28, s[4:5], 0, v28, s[4:5]
	v_add_f32_e32 v29, v30, v29
	v_sub_u32_e32 v30, 0, v28
	v_cvt_f32_i32_e32 v28, v28
	v_ldexp_f32 v8, v8, v30
	v_ldexp_f32 v29, v29, v30
	v_add_f32_e32 v30, -1.0, v8
	v_add_f32_e32 v31, 1.0, v8
	v_add_f32_e32 v32, 1.0, v30
	v_add_f32_e32 v33, -1.0, v31
	v_sub_f32_e32 v32, v8, v32
	v_sub_f32_e32 v8, v8, v33
	v_mul_f32_e32 v33, 0x3f317218, v28
	v_add_f32_e32 v32, v29, v32
	v_add_f32_e32 v8, v29, v8
	v_fma_f32 v29, v28, s20, -v33
	v_add_f32_e32 v34, v30, v32
	v_add_f32_e32 v35, v31, v8
	v_fmac_f32_e32 v29, 0xb102e308, v28
	v_sub_f32_e32 v28, v34, v30
	v_sub_f32_e32 v30, v35, v31
	v_rcp_f32_e32 v31, v35
	v_add_f32_e32 v36, v33, v29
	v_sub_f32_e32 v8, v8, v30
	v_sub_f32_e32 v30, v36, v33
	v_sub_f32_e32 v29, v29, v30
	v_mul_f32_e32 v30, v34, v31
	v_sub_f32_e32 v28, v32, v28
	v_mul_f32_e32 v32, v35, v30
	v_fma_f32 v33, v30, v35, -v32
	v_fmac_f32_e32 v33, v30, v8
	v_add_f32_e32 v37, v32, v33
	v_sub_f32_e32 v38, v34, v37
	v_sub_f32_e32 v32, v37, v32
	v_sub_f32_e32 v34, v34, v38
	v_sub_f32_e32 v32, v32, v33
	v_sub_f32_e32 v33, v34, v37
	v_add_f32_e32 v28, v28, v33
	v_add_f32_e32 v28, v32, v28
	v_add_f32_e32 v32, v38, v28
	v_mul_f32_e32 v33, v31, v32
	v_sub_f32_e32 v34, v38, v32
	v_mul_f32_e32 v37, v35, v33
	v_add_f32_e32 v28, v28, v34
	v_add_f32_e32 v34, v30, v33
	v_fma_f32 v35, v33, v35, -v37
	v_sub_f32_e32 v30, v34, v30
	v_fmac_f32_e32 v35, v33, v8
	v_sub_f32_e32 v8, v33, v30
	v_add_f32_e32 v30, v37, v35
	v_sub_f32_e32 v33, v30, v37
	v_sub_f32_e32 v37, v32, v30
	v_sub_f32_e32 v32, v32, v37
	v_sub_f32_e32 v30, v32, v30
	v_sub_f32_e32 v33, v33, v35
	v_add_f32_e32 v28, v28, v30
	v_add_f32_e32 v28, v33, v28
	v_add_f32_e32 v28, v37, v28
	v_mul_f32_e32 v28, v31, v28
	v_add_f32_e32 v8, v8, v28
	v_add_f32_e32 v28, v34, v8
	v_mul_f32_e32 v30, v28, v28
	v_fmamk_f32 v33, v30, 0x3e9b6dac, v21
	v_sub_f32_e32 v31, v28, v34
	v_ldexp_f32 v32, v28, 1
	v_mul_f32_e32 v28, v28, v30
	v_fmaak_f32 v30, v30, v33, 0x3f2aaada
	v_mul_f32_e32 v28, v28, v30
	v_add_f32_e32 v30, v32, v28
	v_sub_f32_e32 v8, v8, v31
	v_sub_f32_e32 v31, v30, v32
	v_ldexp_f32 v8, v8, 1
	v_sub_f32_e32 v28, v28, v31
	v_add_f32_e32 v8, v8, v28
	v_add_f32_e32 v28, v30, v8
	v_sub_f32_e32 v30, v28, v30
	v_add_f32_e32 v31, v36, v28
	v_sub_f32_e32 v8, v8, v30
	v_sub_f32_e32 v30, v31, v36
	v_sub_f32_e32 v32, v31, v30
	v_sub_f32_e32 v28, v28, v30
	v_add_f32_e32 v30, v29, v8
	v_sub_f32_e32 v32, v36, v32
	v_sub_f32_e32 v33, v30, v29
	v_add_f32_e32 v28, v28, v32
	v_sub_f32_e32 v32, v30, v33
	v_sub_f32_e32 v8, v8, v33
	v_sub_f32_e32 v29, v29, v32
	v_add_f32_e32 v28, v30, v28
	v_add_f32_e32 v8, v8, v29
	v_add_f32_e32 v29, v31, v28
	v_sub_f32_e32 v30, v29, v31
	v_sub_f32_e32 v28, v28, v30
	v_add_f32_e32 v8, v8, v28
	v_add_f32_e32 v8, v29, v8
	v_cmp_neq_f32_e64 s[4:5], s21, v25
	s_nop 1
	v_cndmask_b32_e64 v8, v22, v8, s[4:5]
	v_cmp_ngt_f32_e64 s[4:5], -1.0, v25
	s_nop 1
	v_cndmask_b32_e64 v8, v23, v8, s[4:5]
	v_cmp_neq_f32_e64 s[4:5], -1.0, v25
	s_nop 1
	v_cndmask_b32_e64 v8, v24, v8, s[4:5]
	v_cmp_lt_f32_e64 s[4:5], |v25|, s22
	s_nop 1
	v_cndmask_b32_e64 v8, v8, v25, s[4:5]
	v_sub_f32_e32 v4, v4, v8
	v_mul_f32_e32 v4, 0x3fb8aa3b, v4
	global_store_dword v[26:27], v4, off
	global_load_dwordx4 v[26:29], v[2:3], off
	s_nop 0
	global_load_dwordx4 v[30:33], v[2:3], off offset:16
	global_load_dwordx4 v[34:37], v[2:3], off offset:32
	global_load_dwordx4 v[38:41], v[2:3], off offset:48
	s_waitcnt vmcnt(3)
	v_mov_b32_e32 v2, v27
	v_mov_b32_e32 v3, v28
	v_mov_b32_e32 v27, v29
	s_waitcnt vmcnt(2)
; #define GAS __attribute__((address_space(1)))
; __device__ __forceinline__ void phase_inproj() {
;     ...
;         if (fr_ < 8) {
;           const float bias = ((const GAS float*)P.forget_bias)[fr_];
; #pragma unroll
;           for (int i = 0; i < 4; ++i) {
;             const int row = r0 + fq_ * 4 + i;
;             const GAS f32x4* sp = (const GAS f32x4*)(ssq + (size_t)row * 16);
;             const f32x4 s0 = sp[0], s1 = sp[1], s2 = sp[2], s3 = sp[3];
;             const float t = ((s0.x + s0.y) + (s0.z + s0.w)) + ((s1.x + s1.y) + (s1.z + s1.w)) + ((s2.x + s2.y) + (s2.z + s2.w)) + ((s3.x + s3.y) + (s3.z + s3.w));
;             const float l = c[i] * rsqrtf(t * (1.f / DM) + EPS) + bias;
;             const float ls = fminf(l, 0.f) - log1pf(__expf(-fabsf(l)));
;             logf2[(size_t)((row >> 13) * 8 + fr_) * SEQ + (row & (SEQ - 1))] = ls * LOG2E;
;           }
	v_mov_b32_e32 v28, v31
	v_mov_b32_e32 v29, v32
	v_mov_b32_e32 v31, v33
	v_pk_add_f32 v[2:3], v[2:3], v[26:27]
	v_pk_add_f32 v[26:27], v[28:29], v[30:31]
	v_pk_add_f32 v[2:3], v[2:3], v[2:3] op_sel:[0,1] op_sel_hi:[1,0]
	v_pk_add_f32 v[26:27], v[26:27], v[26:27] op_sel:[0,1] op_sel_hi:[1,0]
	s_waitcnt vmcnt(1)
	v_add_f32_e32 v32, v34, v35
	v_add_f32_e32 v34, v36, v37
	s_waitcnt vmcnt(0)
	v_mov_b32_e32 v33, v40
	v_mov_b32_e32 v35, v41
	v_mov_b32_e32 v3, v38
	v_mov_b32_e32 v27, v39
	v_pk_add_f32 v[28:29], v[32:33], v[34:35]
	v_pk_add_f32 v[2:3], v[2:3], v[26:27]
	s_nop 0
	v_pk_add_f32 v[2:3], v[2:3], v[28:29]
	s_nop 0
	v_add_f32_e32 v2, v2, v3
	v_fmamk_f32 v2, v2, 0x3a800000, v20
	v_mul_f32_e32 v3, 0x4b800000, v2
	v_cmp_gt_f32_e64 s[4:5], s3, v2
	s_nop 1
	v_cndmask_b32_e64 v2, v2, v3, s[4:5]
	v_rsq_f32_e32 v2, v2
	s_nop 0
	v_mul_f32_e32 v3, 0x45800000, v2
	v_cndmask_b32_e64 v2, v2, v3, s[4:5]
	v_fmac_f32_e32 v15, v5, v2
	v_mul_f32_e64 v2, |v15|, s18
	v_exp_f32_e32 v4, v2
	v_bitop3_b32 v2, v14, s26, 3 bitop3:0xc8
	v_lshlrev_b32_e32 v8, 2, v2
	v_min_f32_e32 v5, 0, v15
	v_add_f32_e32 v14, 1.0, v4
	v_add_f32_e32 v15, -1.0, v14
	v_frexp_mant_f32_e32 v25, v14
	v_cvt_f64_f32_e32 v[2:3], v14
	v_sub_f32_e32 v26, v15, v14
	v_frexp_exp_i32_f64_e32 v2, v[2:3]
	v_cmp_gt_f32_e64 s[4:5], s19, v25
	v_sub_f32_e32 v15, v4, v15
	v_add_f32_e32 v3, 1.0, v26
	v_subbrev_co_u32_e64 v2, s[4:5], 0, v2, s[4:5]
	v_add_f32_e32 v3, v15, v3
	v_sub_u32_e32 v15, 0, v2
	v_cvt_f32_i32_e32 v2, v2
	v_ldexp_f32 v14, v14, v15
	v_ldexp_f32 v3, v3, v15
	v_add_f32_e32 v15, -1.0, v14
	v_add_f32_e32 v25, 1.0, v14
	v_add_f32_e32 v26, 1.0, v15
	v_add_f32_e32 v27, -1.0, v25
	v_sub_f32_e32 v26, v14, v26
	v_sub_f32_e32 v14, v14, v27
	v_mul_f32_e32 v27, 0x3f317218, v2
	v_add_f32_e32 v26, v3, v26
	v_add_f32_e32 v3, v3, v14
	v_fma_f32 v14, v2, s20, -v27
	v_add_f32_e32 v28, v15, v26
	v_add_f32_e32 v29, v25, v3
	v_fmac_f32_e32 v14, 0xb102e308, v2
	v_sub_f32_e32 v2, v28, v15
	v_sub_f32_e32 v15, v29, v25
	v_rcp_f32_e32 v25, v29
	v_add_f32_e32 v30, v27, v14
	v_sub_f32_e32 v3, v3, v15
	v_sub_f32_e32 v15, v30, v27
	v_sub_f32_e32 v14, v14, v15
	v_mul_f32_e32 v15, v28, v25
	v_sub_f32_e32 v2, v26, v2
	v_mul_f32_e32 v26, v29, v15
	v_fma_f32 v27, v15, v29, -v26
	v_fmac_f32_e32 v27, v15, v3
	v_add_f32_e32 v31, v26, v27
	v_sub_f32_e32 v32, v28, v31
	v_sub_f32_e32 v26, v31, v26
	v_sub_f32_e32 v28, v28, v32
	v_sub_f32_e32 v26, v26, v27
	v_sub_f32_e32 v27, v28, v31
	v_add_f32_e32 v2, v2, v27
	v_add_f32_e32 v2, v26, v2
	v_add_f32_e32 v26, v32, v2
	v_mul_f32_e32 v27, v25, v26
	v_sub_f32_e32 v28, v32, v26
	v_mul_f32_e32 v31, v29, v27
	v_add_f32_e32 v2, v2, v28
	v_add_f32_e32 v28, v15, v27
	v_fma_f32 v29, v27, v29, -v31
	v_sub_f32_e32 v15, v28, v15
	v_fmac_f32_e32 v29, v27, v3
	v_sub_f32_e32 v3, v27, v15
	v_add_f32_e32 v15, v31, v29
	v_sub_f32_e32 v27, v15, v31
	v_sub_f32_e32 v31, v26, v15
	v_sub_f32_e32 v26, v26, v31
	v_sub_f32_e32 v15, v26, v15
	v_sub_f32_e32 v27, v27, v29
	v_add_f32_e32 v2, v2, v15
	v_add_f32_e32 v2, v27, v2
	v_add_f32_e32 v2, v31, v2
	v_mul_f32_e32 v2, v25, v2
	v_add_f32_e32 v2, v3, v2
	v_add_f32_e32 v3, v28, v2
	v_mul_f32_e32 v15, v3, v3
	v_fmamk_f32 v27, v15, 0x3e9b6dac, v21
	v_sub_f32_e32 v25, v3, v28
	v_ldexp_f32 v26, v3, 1
	v_mul_f32_e32 v3, v3, v15
	v_fmaak_f32 v15, v15, v27, 0x3f2aaada
	v_mul_f32_e32 v3, v3, v15
	v_add_f32_e32 v15, v26, v3
	v_sub_f32_e32 v2, v2, v25
	v_sub_f32_e32 v25, v15, v26
	v_ldexp_f32 v2, v2, 1
	v_sub_f32_e32 v3, v3, v25
	v_add_f32_e32 v2, v2, v3
	v_add_f32_e32 v3, v15, v2
	v_sub_f32_e32 v15, v3, v15
	v_add_f32_e32 v25, v30, v3
	v_sub_f32_e32 v2, v2, v15
	v_sub_f32_e32 v15, v25, v30
	v_sub_f32_e32 v26, v25, v15
	v_sub_f32_e32 v3, v3, v15
	v_add_f32_e32 v15, v14, v2
	v_sub_f32_e32 v26, v30, v26
	v_sub_f32_e32 v27, v15, v14
	v_add_f32_e32 v3, v3, v26
	v_sub_f32_e32 v26, v15, v27
	v_sub_f32_e32 v2, v2, v27
	v_sub_f32_e32 v14, v14, v26
	v_add_f32_e32 v3, v15, v3
	v_add_f32_e32 v2, v2, v14
	v_add_f32_e32 v14, v25, v3
	v_sub_f32_e32 v15, v14, v25
	v_sub_f32_e32 v3, v3, v15
	v_add_f32_e32 v2, v2, v3
	v_add_f32_e32 v2, v14, v2
	v_cmp_neq_f32_e64 s[4:5], s21, v4
	s_nop 1
	v_cndmask_b32_e64 v2, v22, v2, s[4:5]
	v_cmp_ngt_f32_e64 s[4:5], -1.0, v4
	s_nop 1
	v_cndmask_b32_e64 v2, v23, v2, s[4:5]
	v_cmp_neq_f32_e64 s[4:5], -1.0, v4
	s_nop 1
	v_cndmask_b32_e64 v2, v24, v2, s[4:5]
	v_cmp_lt_f32_e64 s[4:5], |v4|, s22
	s_nop 1
	v_cndmask_b32_e64 v2, v2, v4, s[4:5]
	v_sub_f32_e32 v2, v5, v2
	v_mul_f32_e32 v4, 0x3fb8aa3b, v2
	v_lshl_add_u64 v[2:3], v[16:17], 0, v[8:9]
	global_store_dword v[2:3], v4, off
	s_branch .LBB0_377
